# speedup vs baseline: 1.0125x; 1.0125x over previous
; __device__ __forceinline__ unsigned xb_ld(unsigned* p)              { return __hip_atomic_load(p, __ATOMIC_RELAXED, __HIP_MEMORY_SCOPE_AGENT); }
; __device__ __forceinline__ unsigned xb_add(unsigned* p, unsigned v) { return __hip_atomic_fetch_add(p, v, __ATOMIC_RELAXED, __HIP_MEMORY_SCOPE_AGENT); }
; #define XB_SPIN(cond, bar) do { unsigned _sp = 0; while (cond) { __builtin_amdgcn_s_sleep(1); \
;     if ((++_sp & 255u) == 0u) { if (xb_ld(&(bar)[XB_TMO])) break; if (_sp > XB_SPIN_CAP) { atomicAdd(&(bar)[XB_TMO], 1u); break; } } } } while (0)
; __device__ __forceinline__ void xcd_barrier(unsigned* bar, volatile LAS unsigned* st) {
;     ...
;         const unsigned old = xb_add(&bar[XB_XSUB(x)], 1u);
;         const unsigned gen = old / nloc;
;         if (old + 1u == (gen + 1u) * nloc) {
;             __builtin_amdgcn_fence(__ATOMIC_RELEASE, "agent");
;             asm volatile("s_waitcnt vmcnt(0)" ::: "memory");
;             const unsigned og = xb_add(&bar[XB_TOP], 1u);
;             const unsigned tg = og / nx;
;             if (og + 1u == (tg + 1u) * nx) xb_add(&bar[XB_TOPGEN], 1u);
;             else XB_SPIN(xb_ld(&bar[XB_TOPGEN]) == tg, bar);
;             xb_add(&bar[XB_XGEN(x)], 1u);
;             __builtin_amdgcn_fence(__ATOMIC_ACQUIRE, "agent");
;             asm volatile("s_waitcnt vmcnt(0)" ::: "memory");
;         } else {
;             XB_SPIN(xb_ld(&bar[XB_XGEN(x)]) == gen, bar);
;             __builtin_amdgcn_fence(__ATOMIC_ACQUIRE, "agent");
;             asm volatile("s_waitcnt vmcnt(0)" ::: "memory");
;         }
.LBB0_328:
	s_or_b64 exec, exec, s[12:13]
	v_cvt_f32_u32_e32 v5, v3
	s_waitcnt vmcnt(1)
	v_readfirstlane_b32 s10, v4
	s_mov_b32 s99, s98
	v_sub_u32_e32 v4, 0, v3
	v_rcp_iflag_f32_e32 v5, v5
	v_add_u32_e32 v6, s10, v2
	v_mul_f32_e32 v5, 0x4f7ffffe, v5
	v_cvt_u32_f32_e32 v5, v5
	v_mul_lo_u32 v2, v4, v5
	v_mul_hi_u32 v2, v5, v2
	v_add_u32_e32 v2, v5, v2
	v_mul_hi_u32 v2, v6, v2
	v_mul_lo_u32 v4, v2, v3
	v_sub_u32_e32 v4, v6, v4
	v_add_u32_e32 v5, 1, v2
	v_sub_u32_e32 v7, v4, v3
	v_cmp_ge_u32_e32 vcc, v4, v3
	s_nop 1
	v_cndmask_b32_e32 v2, v2, v5, vcc
	v_cndmask_b32_e32 v4, v4, v7, vcc
	v_add_u32_e32 v5, 1, v2
	v_cmp_ge_u32_e32 vcc, v4, v3
	v_add_u32_e32 v4, 1, v6
	s_nop 0
	v_cndmask_b32_e32 v2, v2, v5, vcc
	v_mul_lo_u32 v5, v3, v2
	v_add_u32_e32 v3, v5, v3
	v_cmp_ne_u32_e32 vcc, v4, v3
	s_and_saveexec_b64 s[10:11], vcc
	s_xor_b64 s[10:11], exec, s[10:11]
	s_cbranch_execz .LBB0_342
	s_waitcnt lgkmcnt(0)
	v_mov_b32_e32 v0, 0x2000
	s_lshl_b32 s99, s99, 12
	s_add_u32 s26, s8, 0x2400
	s_addc_u32 s27, s9, 0
	s_sub_u32 s26, s26, s99
	s_subb_u32 s27, s27, 0
	s_cmp_lg_u32 s99, 0
	s_cbranch_scc0 .Lxs_glob_0
	v_add_u32_e32 v2, -1, v3
	global_atomic_or v0, v1, v1, s[26:27] sc0
	s_branch .Lxs_fj_0
.Lxs_glob_0:
	global_load_dword v0, v0, s[8:9] offset:1024 sc1

; __device__ __forceinline__ unsigned xb_ld(unsigned* p)              { return __hip_atomic_load(p, __ATOMIC_RELAXED, __HIP_MEMORY_SCOPE_AGENT); }
; #define XB_SPIN(cond, bar) do { unsigned _sp = 0; while (cond) { __builtin_amdgcn_s_sleep(1); \
;     if ((++_sp & 255u) == 0u) { if (xb_ld(&(bar)[XB_TMO])) break; if (_sp > XB_SPIN_CAP) { atomicAdd(&(bar)[XB_TMO], 1u); break; } } } } while (0)
; __device__ __forceinline__ void xcd_barrier(unsigned* bar, volatile LAS unsigned* st) {
;     ...
;         } else {
;             XB_SPIN(xb_ld(&bar[XB_XGEN(x)]) == gen, bar);
;             __builtin_amdgcn_fence(__ATOMIC_ACQUIRE, "agent");
;             asm volatile("s_waitcnt vmcnt(0)" ::: "memory");
.LBB0_334:
	s_cmp_lg_u32 s99, 0
	s_cbranch_scc1 .Lxs_at_0
	global_load_dword v0, v1, s[26:27] sc1
	s_branch .Lxs_pj_0
.Lxs_at_0:
	global_atomic_or v0, v1, v1, s[26:27] sc0
.Lxs_pj_0:
	s_add_i32 s20, s20, 1
	s_mov_b64 s[44:45], -1
	s_waitcnt vmcnt(0)
	v_cmp_gt_u32_e32 vcc, v0, v2
	s_orn2_b64 s[42:43], vcc, exec
	s_branch .LBB0_331

; __device__ __forceinline__ unsigned xb_ld(unsigned* p)              { return __hip_atomic_load(p, __ATOMIC_RELAXED, __HIP_MEMORY_SCOPE_AGENT); }
; __device__ __forceinline__ unsigned xb_add(unsigned* p, unsigned v) { return __hip_atomic_fetch_add(p, v, __ATOMIC_RELAXED, __HIP_MEMORY_SCOPE_AGENT); }
; #define XB_SPIN(cond, bar) do { unsigned _sp = 0; while (cond) { __builtin_amdgcn_s_sleep(1); \
;     if ((++_sp & 255u) == 0u) { if (xb_ld(&(bar)[XB_TMO])) break; if (_sp > XB_SPIN_CAP) { atomicAdd(&(bar)[XB_TMO], 1u); break; } } } } while (0)
; __device__ __forceinline__ void xcd_barrier(unsigned* bar, volatile LAS unsigned* st) {
;     ...
;         const unsigned old = xb_add(&bar[XB_XSUB(x)], 1u);
;         const unsigned gen = old / nloc;
;         if (old + 1u == (gen + 1u) * nloc) {
;             __builtin_amdgcn_fence(__ATOMIC_RELEASE, "agent");
;             asm volatile("s_waitcnt vmcnt(0)" ::: "memory");
;             const unsigned og = xb_add(&bar[XB_TOP], 1u);
;             const unsigned tg = og / nx;
;             if (og + 1u == (tg + 1u) * nx) xb_add(&bar[XB_TOPGEN], 1u);
;             else XB_SPIN(xb_ld(&bar[XB_TOPGEN]) == tg, bar);
;             xb_add(&bar[XB_XGEN(x)], 1u);
;             __builtin_amdgcn_fence(__ATOMIC_ACQUIRE, "agent");
;             asm volatile("s_waitcnt vmcnt(0)" ::: "memory");
;         } else {
;             XB_SPIN(xb_ld(&bar[XB_XGEN(x)]) == gen, bar);
;             __builtin_amdgcn_fence(__ATOMIC_ACQUIRE, "agent");
;             asm volatile("s_waitcnt vmcnt(0)" ::: "memory");
;         }
.LBB0_421:
	s_or_b64 exec, exec, s[16:17]
	v_cvt_f32_u32_e32 v5, v3
	s_waitcnt vmcnt(1)
	v_readfirstlane_b32 s12, v4
	s_and_b32 s99, s98, s92
	v_sub_u32_e32 v4, 0, v3
	v_rcp_iflag_f32_e32 v5, v5
	v_add_u32_e32 v6, s12, v0
	v_mul_f32_e32 v5, 0x4f7ffffe, v5
	v_cvt_u32_f32_e32 v5, v5
	v_mul_lo_u32 v0, v4, v5
	v_mul_hi_u32 v0, v5, v0
	v_add_u32_e32 v0, v5, v0
	v_mul_hi_u32 v0, v6, v0
	v_mul_lo_u32 v4, v0, v3
	v_sub_u32_e32 v4, v6, v4
	v_add_u32_e32 v5, 1, v0
	v_cmp_ge_u32_e32 vcc, v4, v3
	s_nop 1
	v_cndmask_b32_e32 v0, v0, v5, vcc
	v_sub_u32_e32 v5, v4, v3
	v_cndmask_b32_e32 v4, v4, v5, vcc
	v_add_u32_e32 v5, 1, v0
	v_cmp_ge_u32_e32 vcc, v4, v3
	v_add_u32_e32 v4, 1, v6
	s_nop 0
	v_cndmask_b32_e32 v0, v0, v5, vcc
	v_mul_lo_u32 v5, v3, v0
	v_add_u32_e32 v3, v5, v3
	v_cmp_ne_u32_e32 vcc, v4, v3
	s_and_saveexec_b64 s[12:13], vcc
	s_xor_b64 s[16:17], exec, s[12:13]
	s_cbranch_execz .LBB0_435
	s_waitcnt lgkmcnt(0)
	v_mov_b32_e32 v2, 0x2000
	s_lshl_b32 s99, s99, 12
	s_add_u32 s28, s10, 0x2400
	s_addc_u32 s29, s11, 0
	s_sub_u32 s28, s28, s99
	s_subb_u32 s29, s29, 0
	s_cmp_lg_u32 s99, 0
	s_cbranch_scc0 .Lxs_glob_1
	v_add_u32_e32 v0, -1, v3
	global_atomic_or v2, v1, v1, s[28:29] sc0
	s_branch .Lxs_fj_1
.Lxs_glob_1:
	global_load_dword v2, v2, s[10:11] offset:1024 sc1

; __device__ __forceinline__ unsigned xb_ld(unsigned* p)              { return __hip_atomic_load(p, __ATOMIC_RELAXED, __HIP_MEMORY_SCOPE_AGENT); }
; #define XB_SPIN(cond, bar) do { unsigned _sp = 0; while (cond) { __builtin_amdgcn_s_sleep(1); \
;     if ((++_sp & 255u) == 0u) { if (xb_ld(&(bar)[XB_TMO])) break; if (_sp > XB_SPIN_CAP) { atomicAdd(&(bar)[XB_TMO], 1u); break; } } } } while (0)
; __device__ __forceinline__ void xcd_barrier(unsigned* bar, volatile LAS unsigned* st) {
;     ...
;         } else {
;             XB_SPIN(xb_ld(&bar[XB_XGEN(x)]) == gen, bar);
;             __builtin_amdgcn_fence(__ATOMIC_ACQUIRE, "agent");
;             asm volatile("s_waitcnt vmcnt(0)" ::: "memory");
.LBB0_427:
	s_cmp_lg_u32 s99, 0
	s_cbranch_scc1 .Lxs_at_1
	global_load_dword v2, v1, s[28:29] sc1
	s_branch .Lxs_pj_1
.Lxs_at_1:
	global_atomic_or v2, v1, v1, s[28:29] sc0
.Lxs_pj_1:
	s_add_i32 s20, s20, 1
	s_mov_b64 s[46:47], -1
	s_waitcnt vmcnt(0)
	v_cmp_gt_u32_e32 vcc, v2, v0
	s_orn2_b64 s[44:45], vcc, exec
	s_branch .LBB0_424

; __device__ __forceinline__ unsigned xb_ld(unsigned* p)              { return __hip_atomic_load(p, __ATOMIC_RELAXED, __HIP_MEMORY_SCOPE_AGENT); }
; __device__ __forceinline__ unsigned xb_add(unsigned* p, unsigned v) { return __hip_atomic_fetch_add(p, v, __ATOMIC_RELAXED, __HIP_MEMORY_SCOPE_AGENT); }
; #define XB_SPIN(cond, bar) do { unsigned _sp = 0; while (cond) { __builtin_amdgcn_s_sleep(1); \
;     if ((++_sp & 255u) == 0u) { if (xb_ld(&(bar)[XB_TMO])) break; if (_sp > XB_SPIN_CAP) { atomicAdd(&(bar)[XB_TMO], 1u); break; } } } } while (0)
; __device__ __forceinline__ void xcd_barrier(unsigned* bar, volatile LAS unsigned* st) {
;     ...
;         const unsigned old = xb_add(&bar[XB_XSUB(x)], 1u);
;         const unsigned gen = old / nloc;
;         if (old + 1u == (gen + 1u) * nloc) {
;             __builtin_amdgcn_fence(__ATOMIC_RELEASE, "agent");
;             asm volatile("s_waitcnt vmcnt(0)" ::: "memory");
;             const unsigned og = xb_add(&bar[XB_TOP], 1u);
;             const unsigned tg = og / nx;
;             if (og + 1u == (tg + 1u) * nx) xb_add(&bar[XB_TOPGEN], 1u);
;             else XB_SPIN(xb_ld(&bar[XB_TOPGEN]) == tg, bar);
;             xb_add(&bar[XB_XGEN(x)], 1u);
;             __builtin_amdgcn_fence(__ATOMIC_ACQUIRE, "agent");
;             asm volatile("s_waitcnt vmcnt(0)" ::: "memory");
;         } else {
;             XB_SPIN(xb_ld(&bar[XB_XGEN(x)]) == gen, bar);
;             __builtin_amdgcn_fence(__ATOMIC_ACQUIRE, "agent");
;             asm volatile("s_waitcnt vmcnt(0)" ::: "memory");
;         }
.LBB0_520:
	s_or_b64 exec, exec, s[16:17]
	v_cvt_f32_u32_e32 v5, v3
	s_waitcnt vmcnt(1)
	v_readfirstlane_b32 s12, v4
	s_cmp_lg_u32 s82, 4
	s_cselect_b32 s99, s98, 0
	v_sub_u32_e32 v4, 0, v3
	v_rcp_iflag_f32_e32 v5, v5
	v_add_u32_e32 v6, s12, v0
	v_mul_f32_e32 v5, 0x4f7ffffe, v5
	v_cvt_u32_f32_e32 v5, v5
	v_mul_lo_u32 v0, v4, v5
	v_mul_hi_u32 v0, v5, v0
	v_add_u32_e32 v0, v5, v0
	v_mul_hi_u32 v0, v6, v0
	v_mul_lo_u32 v4, v0, v3
	v_sub_u32_e32 v4, v6, v4
	v_add_u32_e32 v5, 1, v0
	v_cmp_ge_u32_e32 vcc, v4, v3
	s_nop 1
	v_cndmask_b32_e32 v0, v0, v5, vcc
	v_sub_u32_e32 v5, v4, v3
	v_cndmask_b32_e32 v4, v4, v5, vcc
	v_add_u32_e32 v5, 1, v0
	v_cmp_ge_u32_e32 vcc, v4, v3
	v_add_u32_e32 v4, 1, v6
	s_nop 0
	v_cndmask_b32_e32 v0, v0, v5, vcc
	v_mul_lo_u32 v5, v3, v0
	v_add_u32_e32 v3, v5, v3
	v_cmp_ne_u32_e32 vcc, v4, v3
	s_and_saveexec_b64 s[12:13], vcc
	s_xor_b64 s[16:17], exec, s[12:13]
	s_cbranch_execz .LBB0_534
	s_waitcnt lgkmcnt(0)
	v_mov_b32_e32 v2, 0x2000
	s_lshl_b32 s99, s99, 12
	s_add_u32 s28, s10, 0x2400
	s_addc_u32 s29, s11, 0
	s_sub_u32 s28, s28, s99
	s_subb_u32 s29, s29, 0
	s_cmp_lg_u32 s99, 0
	s_cbranch_scc0 .Lxs_glob_2
	v_add_u32_e32 v0, -1, v3
	global_atomic_or v2, v1, v1, s[28:29] sc0
	s_branch .Lxs_fj_2

; __device__ __forceinline__ unsigned xb_ld(unsigned* p)              { return __hip_atomic_load(p, __ATOMIC_RELAXED, __HIP_MEMORY_SCOPE_AGENT); }
; __device__ __forceinline__ unsigned xb_add(unsigned* p, unsigned v) { return __hip_atomic_fetch_add(p, v, __ATOMIC_RELAXED, __HIP_MEMORY_SCOPE_AGENT); }
; #define XB_SPIN(cond, bar) do { unsigned _sp = 0; while (cond) { __builtin_amdgcn_s_sleep(1); \
;     if ((++_sp & 255u) == 0u) { if (xb_ld(&(bar)[XB_TMO])) break; if (_sp > XB_SPIN_CAP) { atomicAdd(&(bar)[XB_TMO], 1u); break; } } } } while (0)
; __device__ __forceinline__ void xcd_barrier(unsigned* bar, volatile LAS unsigned* st) {
;     ...
;         const unsigned old = xb_add(&bar[XB_XSUB(x)], 1u);
;         const unsigned gen = old / nloc;
;         if (old + 1u == (gen + 1u) * nloc) {
;             __builtin_amdgcn_fence(__ATOMIC_RELEASE, "agent");
;             asm volatile("s_waitcnt vmcnt(0)" ::: "memory");
;             const unsigned og = xb_add(&bar[XB_TOP], 1u);
;             const unsigned tg = og / nx;
;             if (og + 1u == (tg + 1u) * nx) xb_add(&bar[XB_TOPGEN], 1u);
;             else XB_SPIN(xb_ld(&bar[XB_TOPGEN]) == tg, bar);
;             xb_add(&bar[XB_XGEN(x)], 1u);
;             __builtin_amdgcn_fence(__ATOMIC_ACQUIRE, "agent");
;             asm volatile("s_waitcnt vmcnt(0)" ::: "memory");
;         } else {
;             XB_SPIN(xb_ld(&bar[XB_XGEN(x)]) == gen, bar);
;             __builtin_amdgcn_fence(__ATOMIC_ACQUIRE, "agent");
;             asm volatile("s_waitcnt vmcnt(0)" ::: "memory");
;         }
.LBB0_604:
	s_or_b64 exec, exec, s[16:17]
	v_cvt_f32_u32_e32 v5, v3
	s_waitcnt vmcnt(1)
	v_readfirstlane_b32 s12, v4
	s_mov_b32 s99, s98
	v_sub_u32_e32 v4, 0, v3
	v_rcp_iflag_f32_e32 v5, v5
	v_add_u32_e32 v6, s12, v0
	v_mul_f32_e32 v5, 0x4f7ffffe, v5
	v_cvt_u32_f32_e32 v5, v5
	v_mul_lo_u32 v0, v4, v5
	v_mul_hi_u32 v0, v5, v0
	v_add_u32_e32 v0, v5, v0
	v_mul_hi_u32 v0, v6, v0
	v_mul_lo_u32 v4, v0, v3
	v_sub_u32_e32 v4, v6, v4
	v_add_u32_e32 v5, 1, v0
	v_cmp_ge_u32_e32 vcc, v4, v3
	s_nop 1
	v_cndmask_b32_e32 v0, v0, v5, vcc
	v_sub_u32_e32 v5, v4, v3
	v_cndmask_b32_e32 v4, v4, v5, vcc
	v_add_u32_e32 v5, 1, v0
	v_cmp_ge_u32_e32 vcc, v4, v3
	v_add_u32_e32 v4, 1, v6
	s_nop 0
	v_cndmask_b32_e32 v0, v0, v5, vcc
	v_mul_lo_u32 v5, v3, v0
	v_add_u32_e32 v3, v5, v3
	v_cmp_ne_u32_e32 vcc, v4, v3
	s_and_saveexec_b64 s[12:13], vcc
	s_xor_b64 s[16:17], exec, s[12:13]
	s_cbranch_execz .LBB0_618
	s_waitcnt lgkmcnt(0)
	v_mov_b32_e32 v2, 0x2000
	s_lshl_b32 s99, s99, 12
	s_add_u32 s28, s10, 0x2400
	s_addc_u32 s29, s11, 0
	s_sub_u32 s28, s28, s99
	s_subb_u32 s29, s29, 0
	s_cmp_lg_u32 s99, 0
	s_cbranch_scc0 .Lxs_glob_3
	v_add_u32_e32 v0, -1, v3
	global_atomic_or v2, v1, v1, s[28:29] sc0
	s_branch .Lxs_fj_3
